# attention V phase: row-max tree removed from the common path (exps out-of-place into dead K/V fragment registers; tile row-sum >= 240 triggers the original max/shift path with exps redone; results unc
# speedup vs baseline: 1.0070x; 1.0070x over previous
; #define RESC(al) do { if (__any((al) < 1.f)) { if (hi == 0) al_l[r32] = (al); asm volatile("s_waitcnt lgkmcnt(0)" ::: "memory"); \
;         _Pragma("unroll") for (int d_ = 0; d_ < 2; ++d_) _Pragma("unroll") for (int r = 0; r < 16; ++r) o[d_][r] *= al_l[crow(r, hi)]; } } while (0)
; #define MASKT(P0_, P1_, t) do { const int kbm_ = TT(t) * 64; if (kbm_ + 63 > qlo) mask_tile(P0_, P1_, qm - kbm_); } while (0)
; #define SHIFT(P0_, P1_, dl_) do { m_reg += (dl_); _Pragma("unroll") for (int r = 0; r < 16; ++r) { P0_[r] -= (dl_); P1_[r] -= (dl_); } _Pragma("unroll") for (int r = 0; r < 16; ++r) negm[r] = -m_reg; } while (0)
; template <int VAR> __device__ __forceinline__ void block(const bf16* Q, const bf16* KVB, const bf16* KR, const float* cosT, bf16* OB, LAS unsigned char* lds, int b, int h, int qb, int t0, int wv, ...
;     ...
;         MASKT(px0, px1, t);
;         float pm_, alX = 1.f; ROWMAX(px0, px1, pm_);
;         if (__builtin_expect(__any(pm_ > THR), 0)) { const float dl_ = fmaxf(pm_, 0.f); SHIFT(px0, px1, dl_); alX = __builtin_amdgcn_exp2f(-dl_); }
;         TILE_VALU(alX);
;         pa0 = pn0; pa1 = pn1; pa2 = pn2; pa3 = pn3;
;         RESC(alX);
;         sk = (sk + 1) & 3; sv = (sv + 1) & 3;
.LBB0_1418:
	v_exp_f32_e32 v190, v64
	v_exp_f32_e32 v194, v68
	v_exp_f32_e32 v174, v48
	v_exp_f32_e32 v178, v52
	v_exp_f32_e32 v191, v65
	v_exp_f32_e32 v195, v69
	v_exp_f32_e32 v175, v49
	v_exp_f32_e32 v179, v53
	v_exp_f32_e32 v192, v66
	v_exp_f32_e32 v196, v70
	v_exp_f32_e32 v176, v50
	v_exp_f32_e32 v180, v54
	v_exp_f32_e32 v193, v67
	v_exp_f32_e32 v197, v71
	v_exp_f32_e32 v177, v51
	v_exp_f32_e32 v181, v55
	v_exp_f32_e32 v198, v72
	v_exp_f32_e32 v182, v56
	v_add_f32_e32 v96, v174, v190
	v_add_f32_e32 v100, v178, v194
	v_exp_f32_e32 v199, v73
	v_exp_f32_e32 v183, v57
	v_add_f32_e32 v97, v175, v191
	v_add_f32_e32 v96, v96, v100
	v_add_f32_e32 v100, v179, v195
	v_exp_f32_e32 v200, v74
	v_exp_f32_e32 v184, v58
	v_add_f32_e32 v98, v176, v192
	v_add_f32_e32 v97, v97, v100
	v_add_f32_e32 v100, v180, v196
	v_exp_f32_e32 v201, v75
	v_exp_f32_e32 v185, v59
	v_add_f32_e32 v99, v177, v193
	v_add_f32_e32 v98, v98, v100
	v_add_f32_e32 v100, v181, v197
	v_exp_f32_e32 v202, v76
	v_exp_f32_e32 v186, v60
	v_add_f32_e32 v99, v99, v100
	v_add_f32_e32 v100, v182, v198
	v_exp_f32_e32 v203, v77
	v_exp_f32_e32 v187, v61
	v_add_f32_e32 v96, v100, v96
	v_add_f32_e32 v100, v183, v199
	v_exp_f32_e32 v204, v78
	v_exp_f32_e32 v188, v62
	v_add_f32_e32 v97, v100, v97
	v_add_f32_e32 v100, v184, v200
	v_exp_f32_e32 v205, v79
	v_exp_f32_e32 v189, v63
	v_add_f32_e32 v98, v100, v98
	v_add_f32_e32 v100, v185, v201
	v_add_f32_e32 v99, v100, v99
	v_add_f32_e32 v100, v186, v202
	v_add_f32_e32 v96, v100, v96
	v_add_f32_e32 v100, v187, v203
	v_add_f32_e32 v97, v100, v97
	v_add_f32_e32 v100, v188, v204
	v_add_f32_e32 v98, v100, v98
	v_add_f32_e32 v100, v189, v205
	v_add_f32_e32 v99, v100, v99
	v_add_f32_e32 v96, v96, v97
	v_add_f32_e32 v97, v98, v99
	v_add_f32_e32 v96, v96, v97
	v_cmp_le_f32_e32 vcc, 0x43700000, v96
	v_mov_b32_e32 v97, v96
	v_cvt_pk_bf16_f32 v140, v190, v191
	v_cvt_pk_bf16_f32 v141, v192, v193
	v_permlane32_swap_b32_e32 v96, v97
	v_add_f32_e32 v96, v96, v97
	s_cbranch_vccnz .Lat_slow
.Lat_vjoin:
	v_add_f32_e32 v150, v150, v96
.LBB0_1422:
	s_add_i32 s4, s82, 1
	s_and_b32 s82, s4, 3
	s_add_i32 s4, s68, 1
	s_add_i32 s85, s85, 1
	s_and_b32 s68, s4, 3
	s_add_i32 s4, s67, s85
	s_add_i32 s33, s33, 64
	v_subrev_u32_e32 v173, 64, v173
	v_lshl_add_u64 v[154:155], v[154:155], 0, s[94:95]
	v_lshl_add_u64 v[156:157], v[156:157], 0, s[70:71]
	v_lshl_add_u64 v[158:159], v[158:159], 0, s[94:95]
	v_cvt_pk_bf16_f32 v142, v194, v195
	v_cvt_pk_bf16_f32 v143, v196, v197
	v_cvt_pk_bf16_f32 v136, v198, v199
	v_cvt_pk_bf16_f32 v137, v200, v201
	v_cvt_pk_bf16_f32 v138, v202, v203
	v_cvt_pk_bf16_f32 v139, v204, v205
	v_cvt_pk_bf16_f32 v132, v174, v175
	v_cvt_pk_bf16_f32 v133, v176, v177
	v_cvt_pk_bf16_f32 v134, v178, v179
	v_cvt_pk_bf16_f32 v135, v180, v181
	v_cvt_pk_bf16_f32 v128, v182, v183
	v_cvt_pk_bf16_f32 v129, v184, v185
	v_cvt_pk_bf16_f32 v130, v186, v187
	v_cvt_pk_bf16_f32 v131, v188, v189
	s_cmp_eq_u32 s4, 4
	s_cbranch_scc1 .LBB0_1430
	s_cmp_ge_u32 s85, s66
	s_cselect_b64 s[4:5], -1, 0
	s_cbranch_scc1 .Lat_mbar0
	s_waitcnt vmcnt(6) lgkmcnt(0)
	s_barrier
	s_branch .Lat_mreads

.Lat_slow:
	v_max3_f32 v128, v48, v64, v49
	v_max3_f32 v129, v65, v50, v66
	v_max3_f32 v130, v51, v67, v52
	v_max3_f32 v131, v68, v53, v69
	v_max3_f32 v128, v128, v54, v70
	v_max3_f32 v129, v129, v55, v71
	v_max3_f32 v130, v130, v56, v72
	v_max3_f32 v131, v131, v57, v73
	v_max3_f32 v128, v128, v58, v74
	v_max3_f32 v129, v129, v59, v75
	v_max3_f32 v130, v130, v60, v76
	v_max3_f32 v131, v131, v61, v77
	v_max3_f32 v128, v128, v62, v78
	v_max3_f32 v129, v129, v63, v79
	v_max3_f32 v128, v128, v129, v130
	v_max_f32_e32 v128, v128, v131
	v_mov_b32_e32 v129, v128
	s_nop 1
	v_permlane32_swap_b32_e32 v128, v129
	v_max_f32_e32 v129, v128, v129
	s_mov_b32 s4, 0x41000000
	v_cmp_lt_f32_e32 vcc, s4, v129
	s_mov_b32 s5, 0
	s_cbranch_vccz .Lat_sexp
	v_max_f32_e32 v32, v129, v129
	v_max_f32_e32 v34, 0, v32
	v_exp_f32_e64 v128, -v34
	v_add_f32_e32 v151, v151, v34
	v_xor_b32_e32 v32, 0x80000000, v151
	v_pk_add_f32 v[64:65], v[64:65], v[34:35] op_sel_hi:[1,0] neg_lo:[0,1] neg_hi:[0,1]
	v_pk_add_f32 v[48:49], v[48:49], v[34:35] op_sel_hi:[1,0] neg_lo:[0,1] neg_hi:[0,1]
	v_pk_add_f32 v[66:67], v[66:67], v[34:35] op_sel_hi:[1,0] neg_lo:[0,1] neg_hi:[0,1]
	v_pk_add_f32 v[50:51], v[50:51], v[34:35] op_sel_hi:[1,0] neg_lo:[0,1] neg_hi:[0,1]
	v_pk_add_f32 v[68:69], v[68:69], v[34:35] op_sel_hi:[1,0] neg_lo:[0,1] neg_hi:[0,1]
	v_pk_add_f32 v[52:53], v[52:53], v[34:35] op_sel_hi:[1,0] neg_lo:[0,1] neg_hi:[0,1]
	v_pk_add_f32 v[70:71], v[70:71], v[34:35] op_sel_hi:[1,0] neg_lo:[0,1] neg_hi:[0,1]
	v_pk_add_f32 v[54:55], v[54:55], v[34:35] op_sel_hi:[1,0] neg_lo:[0,1] neg_hi:[0,1]
	v_pk_add_f32 v[72:73], v[72:73], v[34:35] op_sel_hi:[1,0] neg_lo:[0,1] neg_hi:[0,1]
	v_pk_add_f32 v[56:57], v[56:57], v[34:35] op_sel_hi:[1,0] neg_lo:[0,1] neg_hi:[0,1]
	v_pk_add_f32 v[74:75], v[74:75], v[34:35] op_sel_hi:[1,0] neg_lo:[0,1] neg_hi:[0,1]
	v_pk_add_f32 v[58:59], v[58:59], v[34:35] op_sel_hi:[1,0] neg_lo:[0,1] neg_hi:[0,1]
	v_pk_add_f32 v[76:77], v[76:77], v[34:35] op_sel_hi:[1,0] neg_lo:[0,1] neg_hi:[0,1]
	v_pk_add_f32 v[60:61], v[60:61], v[34:35] op_sel_hi:[1,0] neg_lo:[0,1] neg_hi:[0,1]
	v_pk_add_f32 v[78:79], v[78:79], v[34:35] op_sel_hi:[1,0] neg_lo:[0,1] neg_hi:[0,1]
	v_pk_add_f32 v[62:63], v[62:63], v[34:35] op_sel_hi:[1,0] neg_lo:[0,1] neg_hi:[0,1]
	v_mov_b32_e32 v33, v32
	v_mov_b32_e32 v34, v32
	v_mov_b32_e32 v35, v32
	v_mov_b32_e32 v36, v32
	v_mov_b32_e32 v37, v32
	v_mov_b32_e32 v38, v32
	v_mov_b32_e32 v39, v32
	v_mov_b32_e32 v40, v32
	v_mov_b32_e32 v41, v32
	v_mov_b32_e32 v42, v32
	v_mov_b32_e32 v43, v32
	v_mov_b32_e32 v44, v32
	v_mov_b32_e32 v45, v32
	v_mov_b32_e32 v46, v32
	v_mov_b32_e32 v47, v32
	s_mov_b32 s5, 1
.Lat_sexp:
	v_exp_f32_e32 v190, v64
	v_exp_f32_e32 v194, v68
	v_exp_f32_e32 v174, v48
	v_exp_f32_e32 v178, v52
	v_exp_f32_e32 v191, v65
	v_exp_f32_e32 v195, v69
	v_exp_f32_e32 v175, v49
	v_exp_f32_e32 v179, v53
	v_exp_f32_e32 v192, v66
	v_exp_f32_e32 v196, v70
	v_exp_f32_e32 v176, v50
	v_exp_f32_e32 v180, v54
	v_exp_f32_e32 v193, v67
	v_exp_f32_e32 v197, v71
	v_exp_f32_e32 v177, v51
	v_exp_f32_e32 v181, v55
	v_exp_f32_e32 v198, v72
	v_exp_f32_e32 v182, v56
	v_add_f32_e32 v96, v174, v190
	v_add_f32_e32 v100, v178, v194
	v_exp_f32_e32 v199, v73
	v_exp_f32_e32 v183, v57
	v_add_f32_e32 v97, v175, v191
	v_add_f32_e32 v96, v96, v100
	v_add_f32_e32 v100, v179, v195
	v_exp_f32_e32 v200, v74
	v_exp_f32_e32 v184, v58
	v_add_f32_e32 v98, v176, v192
	v_add_f32_e32 v97, v97, v100
	v_add_f32_e32 v100, v180, v196
	v_exp_f32_e32 v201, v75
	v_exp_f32_e32 v185, v59
	v_add_f32_e32 v99, v177, v193
	v_add_f32_e32 v98, v98, v100
	v_add_f32_e32 v100, v181, v197
	v_exp_f32_e32 v202, v76
	v_exp_f32_e32 v186, v60
	v_add_f32_e32 v99, v99, v100
	v_add_f32_e32 v100, v182, v198
	v_exp_f32_e32 v203, v77
	v_exp_f32_e32 v187, v61
	v_add_f32_e32 v96, v100, v96
	v_add_f32_e32 v100, v183, v199
	v_exp_f32_e32 v204, v78
	v_exp_f32_e32 v188, v62
	v_add_f32_e32 v97, v100, v97
	v_add_f32_e32 v100, v184, v200
	v_exp_f32_e32 v205, v79
	v_exp_f32_e32 v189, v63
	v_add_f32_e32 v98, v100, v98
	v_add_f32_e32 v100, v185, v201
	v_add_f32_e32 v99, v100, v99
	v_add_f32_e32 v100, v186, v202
	v_add_f32_e32 v96, v100, v96
	v_add_f32_e32 v100, v187, v203
	v_add_f32_e32 v97, v100, v97
	v_add_f32_e32 v100, v188, v204
	v_add_f32_e32 v98, v100, v98
	v_add_f32_e32 v100, v189, v205
	v_add_f32_e32 v99, v100, v99
	v_add_f32_e32 v96, v96, v97
	v_add_f32_e32 v97, v98, v99
	v_add_f32_e32 v96, v96, v97
	v_mov_b32_e32 v97, v96
	v_cvt_pk_bf16_f32 v140, v190, v191
	v_cvt_pk_bf16_f32 v141, v192, v193
	v_permlane32_swap_b32_e32 v96, v97
	v_add_f32_e32 v96, v96, v97
	s_cmp_lg_u32 s5, 0
	s_cbranch_scc1 .Lat_resc
	s_branch .Lat_vjoin
; #define SBAR() __builtin_amdgcn_sched_barrier(0)
; #define WAIT_BAR(N) do { if constexpr (VAR & 4) asm volatile("s_waitcnt vmcnt(" #N ") lgkmcnt(0)" ::: "memory"); else asm volatile("s_waitcnt vmcnt(" #N ") lgkmcnt(0)\n\ts_barrier" ::: "memory"); } while (0)
; #define RESC(al) do { if (__any((al) < 1.f)) { if (hi == 0) al_l[r32] = (al); asm volatile("s_waitcnt lgkmcnt(0)" ::: "memory"); \
;         _Pragma("unroll") for (int d_ = 0; d_ < 2; ++d_) _Pragma("unroll") for (int r = 0; r < 16; ++r) o[d_][r] *= al_l[crow(r, hi)]; } } while (0)
; #define VREAD(slot) do { const int vb_ = vb0 + (slot) * VSLOT; \
;         TRRD(vl[0], 0); TRRD(vh[0], 512); TRRD(vl[1], 1024); TRRD(vh[1], 1536); TRRD(vl[2], 2048); TRRD(vh[2], 2560); TRRD(vl[3], 3072); TRRD(vh[3], 3584); \
;         TRRD(vl[4], 4096); TRRD(vh[4], 4608); TRRD(vl[5], 5120); TRRD(vh[5], 5632); TRRD(vl[6], 6144); TRRD(vh[6], 6656); TRRD(vl[7], 7168); TRRD(vh[7], 7680); } while (0)
; template <int VAR> __device__ __forceinline__ void block(const bf16* Q, const bf16* KVB, const bf16* KR, const float* cosT, bf16* OB, LAS unsigned char* lds, int b, int h, int qb, int t0, int wv, ...
;     ...
;         RESC(alX);
;         sk = (sk + 1) & 3; sv = (sv + 1) & 3;
;     }
;     WAIT_BAR(0);
;     VREAD(sv); asm volatile("s_waitcnt lgkmcnt(0)" ::: "memory"); SBAR(); PVALL();
;     if (!trail) WAIT_BAR(0);
;     if (has_next) PRIME(nb_, nh_, nqb_);
.Lat_resc:
	v_fma_f32 v150, v150, v128, v96
	s_and_saveexec_b64 s[4:5], s[2:3]
	ds_write_b32 v171, v128 offset:128
	s_or_b64 exec, exec, s[4:5]
	s_waitcnt lgkmcnt(0)
	ds_read_b128 v[80:83], v168 offset:224
	ds_read_b128 v[84:87], v168 offset:192
	ds_read_b128 v[88:91], v168 offset:160
	ds_read_b128 v[92:95], v168 offset:128
	s_waitcnt lgkmcnt(0)
	v_pk_mul_f32 v[30:31], v[30:31], v[82:83]
	v_pk_mul_f32 v[26:27], v[26:27], v[86:87]
	v_pk_mul_f32 v[22:23], v[22:23], v[90:91]
	v_pk_mul_f32 v[18:19], v[18:19], v[94:95]
	v_pk_mul_f32 v[28:29], v[28:29], v[80:81]
	v_pk_mul_f32 v[24:25], v[24:25], v[84:85]
	v_pk_mul_f32 v[20:21], v[20:21], v[88:89]
	v_pk_mul_f32 v[16:17], v[16:17], v[92:93]
	v_pk_mul_f32 v[14:15], v[14:15], v[82:83]
	v_pk_mul_f32 v[10:11], v[10:11], v[86:87]
	v_pk_mul_f32 v[6:7], v[6:7], v[90:91]
	v_pk_mul_f32 v[2:3], v[2:3], v[94:95]
	v_pk_mul_f32 v[12:13], v[12:13], v[80:81]
	v_pk_mul_f32 v[8:9], v[8:9], v[84:85]
	v_pk_mul_f32 v[4:5], v[4:5], v[88:89]
	v_pk_mul_f32 v[0:1], v[0:1], v[92:93]
	s_branch .LBB0_1422
.LBB0_1427:
	s_waitcnt vmcnt(0) lgkmcnt(0)
	s_barrier
	s_branch .LBB0_1415
.LBB0_1430:
	s_waitcnt vmcnt(0) lgkmcnt(0)
	s_barrier
	v_lshl_add_u32 v49, s68, 13, v172
	ds_read_b64_tr_b16 v[32:33], v49 offset:0
	ds_read_b64_tr_b16 v[34:35], v49 offset:0x200
	ds_read_b64_tr_b16 v[36:37], v49 offset:0x400
	ds_read_b64_tr_b16 v[38:39], v49 offset:0x600
	ds_read_b64_tr_b16 v[40:41], v49 offset:0x800
	ds_read_b64_tr_b16 v[42:43], v49 offset:0xa00
	ds_read_b64_tr_b16 v[44:45], v49 offset:0xc00
	ds_read_b64_tr_b16 v[46:47], v49 offset:0xe00
	ds_read_b64_tr_b16 v[50:51], v49 offset:0x1000
	ds_read_b64_tr_b16 v[52:53], v49 offset:0x1200
	ds_read_b64_tr_b16 v[54:55], v49 offset:0x1400
	ds_read_b64_tr_b16 v[56:57], v49 offset:0x1600
	ds_read_b64_tr_b16 v[58:59], v49 offset:0x1800
	ds_read_b64_tr_b16 v[60:61], v49 offset:0x1a00
	ds_read_b64_tr_b16 v[62:63], v49 offset:0x1c00
	ds_read_b64_tr_b16 v[64:65], v49 offset:0x1e00
	s_waitcnt lgkmcnt(0)
	s_nop 0
	v_mfma_f32_32x32x16_bf16 v[16:31], v[140:143], v[32:35], v[16:31]
	v_readlane_b32 s4, v254, 25
	v_readlane_b32 s5, v254, 26
	s_and_b64 vcc, exec, s[4:5]
	v_mfma_f32_32x32x16_bf16 v[0:15], v[140:143], v[50:53], v[0:15]
	v_mfma_f32_32x32x16_bf16 v[16:31], v[136:139], v[36:39], v[16:31]
	v_mfma_f32_32x32x16_bf16 v[0:15], v[136:139], v[54:57], v[0:15]
	v_mfma_f32_32x32x16_bf16 v[16:31], v[132:135], v[40:43], v[16:31]
	v_mfma_f32_32x32x16_bf16 v[0:15], v[132:135], v[58:61], v[0:15]
	v_mfma_f32_32x32x16_bf16 v[16:31], v[128:131], v[44:47], v[16:31]
	v_mfma_f32_32x32x16_bf16 v[0:15], v[128:131], v[62:65], v[0:15]
	s_cbranch_vccz .LBB0_1432
	s_waitcnt vmcnt(0) lgkmcnt(0)
	s_barrier
